# v26 + no store drain between the mixer-interval gate GEMM and the pooling items + single-counter fast path for the two local seams
# baseline (speedup 1.0000x reference)
.LBB0_389:
	v_readlane_b32 s0, v251, 1
	v_readlane_b32 s1, v251, 2
	s_andn2_b64 vcc, exec, s[0:1]
	v_readlane_b32 s36, v250, 15
	v_readlane_b32 s5, v250, 18
	s_mov_b32 s46, s76
	s_barrier
	s_cbranch_vccnz .LBB0_463
	v_and_b32_e32 v6, 15, v186
	v_and_b32_e32 v7, -16, v186
	v_ashrrev_i32_e32 v11, 4, v186
	s_movk_i32 s0, 0x210
	v_lshl_add_u32 v2, v6, 8, v7
	v_mov_b32_e32 v3, v27
	v_mul_lo_u32 v12, v11, s7
	v_mul_lo_u32 v11, v11, s0
	v_readlane_b32 s0, v251, 42
	v_lshl_add_u64 v[4:5], s[38:39], 0, v[2:3]
	s_lshl_b32 s68, s0, 1
	v_lshl_add_u64 v[102:103], v[4:5], 0, s[68:69]
	s_mov_b64 s[0:1], 0x1000
	v_lshl_add_u64 v[104:105], v[102:103], 0, s[0:1]
	s_mov_b64 s[0:1], 0x1040
	v_lshl_add_u64 v[106:107], v[102:103], 0, s[0:1]
	s_mov_b64 s[0:1], 0x1080
	v_lshl_add_u64 v[108:109], v[102:103], 0, s[0:1]
	s_mov_b64 s[0:1], 0x10c0
	v_lshl_add_u64 v[110:111], v[102:103], 0, s[0:1]
	v_readlane_b32 s0, v251, 57
	v_readlane_b32 s4, v253, 45
	s_add_u32 s0, s0, s40
	v_readlane_b32 s1, v251, 58
	v_lshlrev_b32_e32 v26, 2, v186
	v_add_u32_e32 v8, s4, v7
	v_mul_u32_u24_e32 v9, 0x110, v6
	v_mul_u32_u24_e32 v10, 0x210, v6
	v_lshl_or_b32 v100, v6, 4, v12
	v_lshl_add_u32 v6, v6, 5, s4
	s_addc_u32 s1, s1, s41
	v_add_u32_e32 v114, s4, v26
	v_mov_b32_e32 v101, v27
	v_lshl_add_u64 v[112:113], s[0:1], 0, v[2:3]
	v_add3_u32 v115, v10, v7, s4
	v_add_u32_e32 v116, v8, v9
	v_add_u32_e32 v117, v6, v11
	v_readlane_b32 s23, v251, 0
	s_branch .LBB0_392
